# v15 + FFN2 down GEMM (fp8) tile order wgm=4 (12 instead of 18 operand streams per XCD round)
# speedup vs baseline: 1.0033x; 1.0008x over previous
.LBB0_1962:
	v_ashrrev_i32_e32 v2, 31, v0
	v_lshrrev_b32_e32 v2, 26, v2
	v_lshlrev_b32_e32 v1, 4, v0
	v_add_u32_e32 v2, v0, v2
	v_bfe_i32 v0, v0, 27, 1
	v_lshrrev_b32_e32 v0, 22, v0
	v_add_u32_e32 v0, v1, v0
	v_and_b32_e32 v0, 0xfffffc00, v0
	v_sub_u32_e32 v0, v1, v0
	v_lshrrev_b32_e32 v3, 4, v0
	v_bitop3_b32 v0, v3, v0, 32 bitop3:0x6c
	v_ashrrev_i32_e32 v4, 31, v0
	v_ashrrev_i32_e32 v2, 6, v2
	v_lshrrev_b32_e32 v4, 26, v4
	v_lshlrev_b32_e32 v3, 3, v2
	v_add_u32_e32 v4, v0, v4
	v_and_b32_e32 v3, -16, v3
	v_ashrrev_i32_e32 v5, 6, v4
	v_and_b32_e32 v4, 0xc0, v4
	v_add_u32_e32 v3, v5, v3
	v_sub_u32_e32 v0, v0, v4
	v_mov_b32_e32 v4, 1
	v_lshlrev_b32_e32 v2, 5, v2
	v_ashrrev_i16_sdwa v0, v4, sext(v0) dst_sel:DWORD dst_unused:UNUSED_PAD src0_sel:DWORD src1_sel:BYTE_0
	v_lshlrev_b32_e32 v6, 1, v3
	v_lshrrev_b32_e32 v7, 2, v3
	v_and_b32_e32 v5, 3, v5
	s_mov_b32 s0, 0xfffe0
	v_and_b32_e32 v2, 32, v2
	v_bfe_i32 v0, v0, 0, 16
	v_and_b32_e32 v6, 24, v6
	v_and_b32_e32 v7, 4, v7
	v_and_or_b32 v5, v3, s0, v5
	v_or3_b32 v5, v5, v7, v6
	v_add_lshl_u32 v0, v2, v0, 1
	v_lshl_add_u32 v160, v3, 12, v0
	v_lshl_add_u32 v162, v5, 12, v0
	v_add_u32_e32 v0, 0x2000, v1
	v_ashrrev_i32_e32 v1, 31, v0
	v_lshrrev_b32_e32 v1, 22, v1
	v_add_u32_e32 v1, v0, v1
	v_ashrrev_i32_e32 v1, 10, v1
	v_mul_i32_i24_e32 v2, 0x400, v1
	v_sub_u32_e32 v0, v0, v2
	v_lshrrev_b32_e32 v2, 4, v0
	v_bitop3_b32 v0, v2, v0, 32 bitop3:0x6c
	v_ashrrev_i32_e32 v3, 31, v0
	v_lshrrev_b32_e32 v3, 26, v3
	s_waitcnt lgkmcnt(0)
	s_add_u32 s23, s2, 0x2fa00000
	v_lshlrev_b32_e32 v2, 3, v1
	v_add_u32_e32 v3, v0, v3
	s_addc_u32 s25, s3, 0
	v_and_b32_e32 v2, -16, v2
	v_ashrrev_i32_e32 v5, 6, v3
	s_add_u32 s26, s2, 0xb400000
	v_add_u32_e32 v2, v5, v2
	v_and_b32_e32 v5, 3, v5
	s_addc_u32 s27, s3, 0
	v_and_or_b32 v5, v2, s0, v5
	s_add_i32 s0, s8, s6
	s_lshr_b32 s6, s0, 6
	s_lshl_b32 s7, s6, 2
	s_and_b32 s1, s0, 3
	s_add_i32 s42, s7, s1
	s_bfe_u32 s6, s0, 0x40002
	s_ashr_i32 s12, s14, 6
	s_ashr_i32 s43, s42, 31
	s_bfe_i64 s[8:9], s[6:7], 0x100000
	v_and_b32_e32 v3, 0xc0, v3
	s_ashr_i32 s15, s14, 8
	s_lshl_b32 s58, s12, 10
	s_lshl_b64 s[0:1], s[42:43], 20
	s_lshl_b64 s[8:9], s[8:9], 20
	v_sub_u32_e32 v0, v0, v3
	s_add_u32 s44, s26, s8
	v_lshlrev_b32_e32 v1, 5, v1
	v_ashrrev_i16_sdwa v0, v4, sext(v0) dst_sel:DWORD dst_unused:UNUSED_PAD src0_sel:DWORD src1_sel:BYTE_0
	v_lshlrev_b32_e32 v3, 1, v2
	v_lshrrev_b32_e32 v4, 2, v2
	s_addc_u32 s45, s27, s9
	s_add_i32 s43, s58, 0
	v_and_b32_e32 v1, 32, v1
	v_bfe_i32 v0, v0, 0, 16
	v_and_b32_e32 v3, 24, v3
	v_and_b32_e32 v4, 4, v4
	v_mov_b32_e32 v180, 0x7f7f7f7f
	s_add_i32 m0, s43, 0x10000
	v_or3_b32 v3, v5, v4, v3
	v_add_lshl_u32 v0, v1, v0, 1
	global_load_lds_dwordx4 v162, s[44:45]
	s_add_i32 m0, s43, 0x12000
	v_lshl_add_u32 v166, v3, 12, v0
	s_add_u32 s8, s44, 0x80000
	global_load_lds_dwordx4 v166, s[44:45]
	s_addc_u32 s9, s45, 0
	s_add_i32 m0, s43, 0x14000
	v_lshl_add_u32 v164, v2, 12, v0
	global_load_lds_dwordx4 v162, s[8:9]
	s_add_i32 m0, s43, 0x16000
	s_add_u32 s46, s23, s0
	s_addc_u32 s47, s25, s1
	s_add_i32 s59, s43, 0x2000
	global_load_lds_dwordx4 v166, s[8:9]
	s_mov_b32 m0, s43
	s_add_u32 s0, s46, 0x80000
	global_load_lds_dwordx4 v160, s[46:47]
	s_mov_b32 m0, s59
	s_addc_u32 s1, s47, 0
	s_add_i32 s60, s43, 0x4000
	global_load_lds_dwordx4 v164, s[46:47]
	s_mov_b32 m0, s60
	s_add_i32 s61, s43, 0x6000
	global_load_lds_dwordx4 v160, s[0:1]
	s_mov_b32 m0, s61
	v_mov_b32_e32 v163, 0
	global_load_lds_dwordx4 v164, s[0:1]
	v_mov_b32_e32 v167, v163
	v_mov_b32_e32 v161, v163
	v_mov_b32_e32 v165, v163
	s_cmp_eq_u32 s15, 1
	s_mov_b32 s7, 0
	v_lshl_add_u64 v[6:7], s[44:45], 0, v[162:163]
	v_lshl_add_u64 v[4:5], s[44:45], 0, v[166:167]
	v_lshl_add_u64 v[0:1], s[46:47], 0, v[160:161]
	s_cselect_b64 s[8:9], -1, 0
	s_cmp_lg_u32 s15, 1
	v_lshl_add_u64 v[2:3], s[46:47], 0, v[164:165]
	s_cbranch_scc1 .LBB0_1964
	s_barrier

.LBB0_1972:
	s_ashr_i32 s0, s6, 3
	s_add_i32 s0, s37, s0
	s_ashr_i32 s1, s0, 31
	s_lshr_b32 s1, s1, 26
	s_add_i32 s1, s0, s1
	s_ashr_i32 s6, s1, 6
	s_lshl_b32 s6, s6, 2
	s_sub_i32 s34, 64, s6
	s_min_i32 s35, s34, 4
	s_abs_i32 s34, s35
	v_cvt_f32_u32_e32 v0, s34
	s_sub_i32 s37, 0, s34
	s_andn2_b32 s1, s1, 63
	s_sub_i32 s0, s0, s1
	v_rcp_iflag_f32_e32 v0, v0
	s_abs_i32 s1, s0
	s_xor_b32 s36, s0, s35
	s_ashr_i32 s36, s36, 31
	v_mul_f32_e32 v0, 0x4f7ffffe, v0
	v_cvt_u32_f32_e32 v0, v0
	s_nop 0
	v_readfirstlane_b32 s38, v0
	s_mul_i32 s37, s37, s38
	s_mul_hi_u32 s37, s38, s37
	s_add_i32 s38, s38, s37
	s_mul_hi_u32 s37, s1, s38
	s_mul_i32 s38, s37, s34
	s_sub_i32 s1, s1, s38
	s_add_i32 s39, s37, 1
	s_sub_i32 s38, s1, s34
	s_cmp_ge_u32 s1, s34
	s_cselect_b32 s37, s39, s37
	s_cselect_b32 s1, s38, s1
	s_add_i32 s38, s37, 1
	s_cmp_ge_u32 s1, s34
	s_cselect_b32 s1, s38, s37
	s_xor_b32 s1, s1, s36
	s_sub_i32 s34, s1, s36
	s_mul_i32 s1, s34, s35
	s_sub_i32 s0, s0, s1
	s_add_i32 s36, s6, s0
